# token0_task: per-lane remainder rows (up to 12 for the last k-slice) loaded together under lane masks instead of one load+wait per row
# speedup vs baseline: 1.0048x; 1.0033x over previous
; DI void token0_task(ldsp lds, const float* xcur, size_t xstride, const float* nw, const float* win, float* q0k0, int task, int tid, int wid, int lane) {
;     ...
;     const float v0 = xr[tid], v1 = xr[tid + 512];
;     const float sq = wave_sum(v0 * v0 + v1 * v1);
;     if (lane == 0) RED[wid] = sq;
;     __syncthreads();
;     float tot = 0.f;
; #pragma unroll
;     for (int i = 0; i < 8; ++i) tot += RED[i];
;     const float rs = rsqrtf(tot * (1.0f / 1024.0f) + 1e-6f);
;     HX[tid] = v0 * rs * nw[tid]; HX[tid + 512] = v1 * rs * nw[tid + 512];
;     __syncthreads();
;     if (tid < 504) {
;         const int g4 = tid % 24, sl = tid / 24, k_lo = sl * 49, k_hi = (k_lo + 49 < 1024) ? k_lo + 49 : 1024;
;         f32x4 acc = (f32x4){0.f, 0.f, 0.f, 0.f};
;         const float* wp = win + (size_t)k_lo * GLA_N + grp * 96 + g4 * 4;
; #pragma unroll 16
;         for (int k = k_lo; k < k_hi; ++k, wp += GLA_N) { const f32x4 w = *(const f32x4*)wp; acc += w * HX[k]; }
.LBB0_813:
	s_or_b64 exec, exec, s[18:19]
	s_waitcnt lgkmcnt(0)
	s_barrier
	ds_read_b128 v[34:37], v12 offset:12160
	ds_read_b128 v[38:41], v12 offset:12176
	s_and_b32 s15, s23, 7
	s_waitcnt lgkmcnt(1)
	v_add_f32_e32 v2, 0, v34
	v_add_f32_e32 v2, v2, v35
	v_add_f32_e32 v2, v2, v36
	v_add_f32_e32 v2, v2, v37
	s_waitcnt lgkmcnt(0)
	v_add_f32_e32 v2, v2, v38
	v_add_f32_e32 v2, v2, v39
	v_add_f32_e32 v2, v2, v40
	v_add_f32_e32 v2, v2, v41
	v_fmamk_f32 v2, v2, 0x3a800000, v231
	v_cmp_gt_f32_e32 vcc, s33, v2
	v_mul_f32_e32 v3, 0x4b800000, v2
	s_nop 0
	v_cndmask_b32_e32 v2, v2, v3, vcc
	v_rsq_f32_e32 v2, v2
	s_nop 0
	v_mul_f32_e32 v3, 0x45800000, v2
	v_cndmask_b32_e32 v2, v2, v3, vcc
	v_mul_f32_e32 v1, v1, v2
	v_mul_f32_e32 v0, v0, v2
	s_waitcnt vmcnt(0)
	v_mul_f32_e32 v1, v224, v1
	v_mul_f32_e32 v0, v225, v0
	ds_write2st64_b32 v22, v1, v0 offset1:8
	s_waitcnt lgkmcnt(0)
	s_barrier
	s_and_saveexec_b64 s[18:19], s[40:41]
	s_cbranch_execz .LBB0_825
	v_mov_b32_e32 v3, 0
	v_mov_b32_e32 v2, 0
	v_mov_b32_e32 v1, 0
	v_mov_b32_e32 v0, 0
	s_and_saveexec_b64 s[26:27], s[42:43]
	s_cbranch_execz .LBB0_824
	v_mov_b32_e32 v13, v12
	s_mul_i32 s0, s15, 0x180
	v_mov_b32_e32 v14, v12
	v_mov_b32_e32 v15, v12
	v_mov_b64_e32 v[0:1], v[12:13]
	v_lshl_add_u64 v[10:11], v[6:7], 0, s[0:1]
	v_mov_b64_e32 v[2:3], v[14:15]
	v_mov_b32_e32 v13, v23
	s_and_saveexec_b64 s[30:31], s[46:47]
	s_cbranch_execz .LBB0_819
	v_mov_b32_e32 v0, 0
	v_mov_b32_e32 v1, v0
	v_mov_b32_e32 v2, v0
	v_mov_b32_e32 v3, v0
	s_mov_b64 s[36:37], exec
	s_mov_b64 s[34:35], 0x2c40
	v_mov_b32_e32 v14, v27
	v_cmp_lt_u32_e32 vcc, 0, v26
	s_and_b64 exec, vcc, s[36:37]
	s_cbranch_execz .Lt0r_issued
	global_load_dwordx4 v[44:47], v[10:11], off
	ds_read_b32 v108, v14
	v_lshl_add_u64 v[10:11], v[10:11], 0, s[34:35]
	v_add_u32_e32 v14, 4, v14
	v_cmp_lt_u32_e32 vcc, 1, v26
	s_and_b64 exec, vcc, s[36:37]
	s_cbranch_execz .Lt0r_issued
	global_load_dwordx4 v[48:51], v[10:11], off
	ds_read_b32 v109, v14
	v_lshl_add_u64 v[10:11], v[10:11], 0, s[34:35]
	v_add_u32_e32 v14, 4, v14
	v_cmp_lt_u32_e32 vcc, 2, v26
	s_and_b64 exec, vcc, s[36:37]
	s_cbranch_execz .Lt0r_issued
	global_load_dwordx4 v[52:55], v[10:11], off
	ds_read_b32 v110, v14
	v_lshl_add_u64 v[10:11], v[10:11], 0, s[34:35]
	v_add_u32_e32 v14, 4, v14
	v_cmp_lt_u32_e32 vcc, 3, v26
	s_and_b64 exec, vcc, s[36:37]
	s_cbranch_execz .Lt0r_issued
	global_load_dwordx4 v[56:59], v[10:11], off
	ds_read_b32 v111, v14
	v_lshl_add_u64 v[10:11], v[10:11], 0, s[34:35]
	v_add_u32_e32 v14, 4, v14
	v_cmp_lt_u32_e32 vcc, 4, v26
	s_and_b64 exec, vcc, s[36:37]
	s_cbranch_execz .Lt0r_issued
	global_load_dwordx4 v[60:63], v[10:11], off
	ds_read_b32 v112, v14
	v_lshl_add_u64 v[10:11], v[10:11], 0, s[34:35]
	v_add_u32_e32 v14, 4, v14
	v_cmp_lt_u32_e32 vcc, 5, v26
	s_and_b64 exec, vcc, s[36:37]
	s_cbranch_execz .Lt0r_issued
	global_load_dwordx4 v[64:67], v[10:11], off
	ds_read_b32 v113, v14
	v_lshl_add_u64 v[10:11], v[10:11], 0, s[34:35]
	v_add_u32_e32 v14, 4, v14
	v_cmp_lt_u32_e32 vcc, 6, v26
	s_and_b64 exec, vcc, s[36:37]
	s_cbranch_execz .Lt0r_issued
	global_load_dwordx4 v[68:71], v[10:11], off
	ds_read_b32 v114, v14
	v_lshl_add_u64 v[10:11], v[10:11], 0, s[34:35]
	v_add_u32_e32 v14, 4, v14
	v_cmp_lt_u32_e32 vcc, 7, v26
	s_and_b64 exec, vcc, s[36:37]
	s_cbranch_execz .Lt0r_issued
	global_load_dwordx4 v[72:75], v[10:11], off
	ds_read_b32 v115, v14
	v_lshl_add_u64 v[10:11], v[10:11], 0, s[34:35]
	v_add_u32_e32 v14, 4, v14
	v_cmp_lt_u32_e32 vcc, 8, v26
	s_and_b64 exec, vcc, s[36:37]
	s_cbranch_execz .Lt0r_issued
	global_load_dwordx4 v[76:79], v[10:11], off
	ds_read_b32 v116, v14
	v_lshl_add_u64 v[10:11], v[10:11], 0, s[34:35]
	v_add_u32_e32 v14, 4, v14
	v_cmp_lt_u32_e32 vcc, 9, v26
	s_and_b64 exec, vcc, s[36:37]
	s_cbranch_execz .Lt0r_issued
	global_load_dwordx4 v[80:83], v[10:11], off
	ds_read_b32 v117, v14
	v_lshl_add_u64 v[10:11], v[10:11], 0, s[34:35]
	v_add_u32_e32 v14, 4, v14
	v_cmp_lt_u32_e32 vcc, 10, v26
	s_and_b64 exec, vcc, s[36:37]
	s_cbranch_execz .Lt0r_issued
	global_load_dwordx4 v[84:87], v[10:11], off
	ds_read_b32 v118, v14
	v_lshl_add_u64 v[10:11], v[10:11], 0, s[34:35]
	v_add_u32_e32 v14, 4, v14
	v_cmp_lt_u32_e32 vcc, 11, v26
	s_and_b64 exec, vcc, s[36:37]
	s_cbranch_execz .Lt0r_issued
	global_load_dwordx4 v[88:91], v[10:11], off
	ds_read_b32 v119, v14
	v_lshl_add_u64 v[10:11], v[10:11], 0, s[34:35]
	v_add_u32_e32 v14, 4, v14
	v_cmp_lt_u32_e32 vcc, 12, v26
	s_and_b64 exec, vcc, s[36:37]
	s_cbranch_execz .Lt0r_issued
	global_load_dwordx4 v[92:95], v[10:11], off
	ds_read_b32 v120, v14
	v_lshl_add_u64 v[10:11], v[10:11], 0, s[34:35]
	v_add_u32_e32 v14, 4, v14
	v_cmp_lt_u32_e32 vcc, 13, v26
	s_and_b64 exec, vcc, s[36:37]
	s_cbranch_execz .Lt0r_issued
	global_load_dwordx4 v[96:99], v[10:11], off
	ds_read_b32 v121, v14
	v_lshl_add_u64 v[10:11], v[10:11], 0, s[34:35]
	v_add_u32_e32 v14, 4, v14
	v_cmp_lt_u32_e32 vcc, 14, v26
	s_and_b64 exec, vcc, s[36:37]
	s_cbranch_execz .Lt0r_issued
	global_load_dwordx4 v[100:103], v[10:11], off
	ds_read_b32 v122, v14
	v_lshl_add_u64 v[10:11], v[10:11], 0, s[34:35]
	v_add_u32_e32 v14, 4, v14
; #define LAS __attribute__((address_space(3)))
; DI void token0_task(ldsp lds, const float* xcur, size_t xstride, const float* nw, const float* win, float* q0k0, int task, int tid, int wid, int lane) {
;     ...
;         for (int k = k_lo; k < k_hi; ++k, wp += GLA_N) { const f32x4 w = *(const f32x4*)wp; acc += w * HX[k]; }
;         *(LAS f32x4*)(PART + sl * 96 + g4 * 4) = acc;
.Lt0r_issued:
	s_mov_b64 exec, s[36:37]
	s_waitcnt vmcnt(0) lgkmcnt(0)
	v_cmp_lt_u32_e32 vcc, 0, v26
	s_and_b64 exec, vcc, s[36:37]
	s_cbranch_execz .Lt0r_done
	v_pk_fma_f32 v[2:3], v[46:47], v[108:109], v[2:3] op_sel_hi:[1,0,1]
	v_pk_fma_f32 v[0:1], v[44:45], v[108:109], v[0:1] op_sel_hi:[1,0,1]
	v_cmp_lt_u32_e32 vcc, 1, v26
	s_and_b64 exec, vcc, s[36:37]
	s_cbranch_execz .Lt0r_done
	v_pk_fma_f32 v[2:3], v[50:51], v[108:109], v[2:3] op_sel:[0,1,0]
	v_pk_fma_f32 v[0:1], v[48:49], v[108:109], v[0:1] op_sel:[0,1,0]
	v_cmp_lt_u32_e32 vcc, 2, v26
	s_and_b64 exec, vcc, s[36:37]
	s_cbranch_execz .Lt0r_done
	v_pk_fma_f32 v[2:3], v[54:55], v[110:111], v[2:3] op_sel_hi:[1,0,1]
	v_pk_fma_f32 v[0:1], v[52:53], v[110:111], v[0:1] op_sel_hi:[1,0,1]
	v_cmp_lt_u32_e32 vcc, 3, v26
	s_and_b64 exec, vcc, s[36:37]
	s_cbranch_execz .Lt0r_done
	v_pk_fma_f32 v[2:3], v[58:59], v[110:111], v[2:3] op_sel:[0,1,0]
	v_pk_fma_f32 v[0:1], v[56:57], v[110:111], v[0:1] op_sel:[0,1,0]
	v_cmp_lt_u32_e32 vcc, 4, v26
	s_and_b64 exec, vcc, s[36:37]
	s_cbranch_execz .Lt0r_done
	v_pk_fma_f32 v[2:3], v[62:63], v[112:113], v[2:3] op_sel_hi:[1,0,1]
	v_pk_fma_f32 v[0:1], v[60:61], v[112:113], v[0:1] op_sel_hi:[1,0,1]
	v_cmp_lt_u32_e32 vcc, 5, v26
	s_and_b64 exec, vcc, s[36:37]
	s_cbranch_execz .Lt0r_done
	v_pk_fma_f32 v[2:3], v[66:67], v[112:113], v[2:3] op_sel:[0,1,0]
	v_pk_fma_f32 v[0:1], v[64:65], v[112:113], v[0:1] op_sel:[0,1,0]
	v_cmp_lt_u32_e32 vcc, 6, v26
	s_and_b64 exec, vcc, s[36:37]
	s_cbranch_execz .Lt0r_done
	v_pk_fma_f32 v[2:3], v[70:71], v[114:115], v[2:3] op_sel_hi:[1,0,1]
	v_pk_fma_f32 v[0:1], v[68:69], v[114:115], v[0:1] op_sel_hi:[1,0,1]
	v_cmp_lt_u32_e32 vcc, 7, v26
	s_and_b64 exec, vcc, s[36:37]
	s_cbranch_execz .Lt0r_done
	v_pk_fma_f32 v[2:3], v[74:75], v[114:115], v[2:3] op_sel:[0,1,0]
	v_pk_fma_f32 v[0:1], v[72:73], v[114:115], v[0:1] op_sel:[0,1,0]
	v_cmp_lt_u32_e32 vcc, 8, v26
	s_and_b64 exec, vcc, s[36:37]
	s_cbranch_execz .Lt0r_done
	v_pk_fma_f32 v[2:3], v[78:79], v[116:117], v[2:3] op_sel_hi:[1,0,1]
	v_pk_fma_f32 v[0:1], v[76:77], v[116:117], v[0:1] op_sel_hi:[1,0,1]
	v_cmp_lt_u32_e32 vcc, 9, v26
	s_and_b64 exec, vcc, s[36:37]
	s_cbranch_execz .Lt0r_done
	v_pk_fma_f32 v[2:3], v[82:83], v[116:117], v[2:3] op_sel:[0,1,0]
	v_pk_fma_f32 v[0:1], v[80:81], v[116:117], v[0:1] op_sel:[0,1,0]
	v_cmp_lt_u32_e32 vcc, 10, v26
	s_and_b64 exec, vcc, s[36:37]
	s_cbranch_execz .Lt0r_done
	v_pk_fma_f32 v[2:3], v[86:87], v[118:119], v[2:3] op_sel_hi:[1,0,1]
	v_pk_fma_f32 v[0:1], v[84:85], v[118:119], v[0:1] op_sel_hi:[1,0,1]
	v_cmp_lt_u32_e32 vcc, 11, v26
	s_and_b64 exec, vcc, s[36:37]
	s_cbranch_execz .Lt0r_done
	v_pk_fma_f32 v[2:3], v[90:91], v[118:119], v[2:3] op_sel:[0,1,0]
	v_pk_fma_f32 v[0:1], v[88:89], v[118:119], v[0:1] op_sel:[0,1,0]
	v_cmp_lt_u32_e32 vcc, 12, v26
	s_and_b64 exec, vcc, s[36:37]
	s_cbranch_execz .Lt0r_done
	v_pk_fma_f32 v[2:3], v[94:95], v[120:121], v[2:3] op_sel_hi:[1,0,1]
	v_pk_fma_f32 v[0:1], v[92:93], v[120:121], v[0:1] op_sel_hi:[1,0,1]
	v_cmp_lt_u32_e32 vcc, 13, v26
	s_and_b64 exec, vcc, s[36:37]
	s_cbranch_execz .Lt0r_done
	v_pk_fma_f32 v[2:3], v[98:99], v[120:121], v[2:3] op_sel:[0,1,0]
	v_pk_fma_f32 v[0:1], v[96:97], v[120:121], v[0:1] op_sel:[0,1,0]
	v_cmp_lt_u32_e32 vcc, 14, v26
	s_and_b64 exec, vcc, s[36:37]
	s_cbranch_execz .Lt0r_done
	v_pk_fma_f32 v[2:3], v[102:103], v[122:123], v[2:3] op_sel_hi:[1,0,1]
	v_pk_fma_f32 v[0:1], v[100:101], v[122:123], v[0:1] op_sel_hi:[1,0,1]
.Lt0r_done:
	s_mov_b64 exec, s[36:37]
	v_mov_b32_e32 v13, v28
